# norm1/norm2 loops: cross-token software pipelining (next token's row loads in flight during current token), norm weights hoisted out of the loop
# speedup vs baseline: 1.0054x; 1.0012x over previous
.LBB0_216:
	s_mov_b64 s[6:7], s[0:1]
	s_mov_b64 s[10:11], s[0:1]
	s_mov_b64 s[14:15], s[0:1]
	s_mov_b64 s[12:13], s[0:1]
	v_mov_b32_e32 v1, v205
	s_mov_b32 s2, s61
	v_mov_b32_e32 v0, v205
	s_lshl_b32 s8, s2, 2
	v_ashrrev_i32_e32 v0, 6, v0
	v_add_u32_e32 v29, s8, v0
	s_movk_i32 s2, 0x5000
	v_readlane_b32 s4, v252, 42
	v_cmp_gt_i32_e32 vcc, s2, v29
	s_mul_hi_u32 s2, s4, 0x1e000
	v_readlane_b32 s5, v252, 43
	v_writelane_b32 v252, s2, 44
	s_mul_i32 s2, s4, 0x1e000
	v_writelane_b32 v252, s2, 45
	s_and_saveexec_b64 s[4:5], vcc
	s_mov_b64 s[18:19], 0x1000
	s_cbranch_execz .LBB0_219
	v_and_b32_e32 v3, 63, v1
	v_and_b32_e32 v1, 64, v216
	v_add_u32_e32 v1, 64, v1
	v_xor_b32_e32 v2, 1, v216
	v_cmp_lt_i32_e32 vcc, v2, v1
	s_load_dwordx2 s[14:15], s[14:15], 0xd0
	s_nop 0
	s_load_dwordx2 s[16:17], s[6:7], 0x100
	s_nop 0
	s_load_dwordx2 s[10:11], s[10:11], 0x108
	s_nop 0
	s_load_dwordx2 s[6:7], s[12:13], 0x108
	v_cndmask_b32_e32 v2, v216, v2, vcc
	v_lshlrev_b32_e32 v34, 2, v2
	v_xor_b32_e32 v2, 2, v216
	v_cmp_lt_i32_e32 vcc, v2, v1
	v_readlane_b32 s12, v252, 40
	v_readlane_b32 s13, v252, 41
	v_cndmask_b32_e32 v2, v216, v2, vcc
	v_lshlrev_b32_e32 v35, 2, v2
	v_xor_b32_e32 v2, 4, v216
	v_cmp_lt_i32_e32 vcc, v2, v1
	s_lshl_b64 s[12:13], s[12:13], 2
	s_waitcnt lgkmcnt(0)
	s_add_u32 s12, s14, s12
	v_cndmask_b32_e32 v2, v216, v2, vcc
	v_lshlrev_b32_e32 v36, 2, v2
	v_xor_b32_e32 v2, 8, v216
	v_cmp_lt_i32_e32 vcc, v2, v1
	s_addc_u32 s13, s15, s13
	v_readlane_b32 s2, v252, 45
	v_cndmask_b32_e32 v2, v216, v2, vcc
	v_lshlrev_b32_e32 v37, 2, v2
	v_xor_b32_e32 v2, 16, v216
	v_cmp_lt_i32_e32 vcc, v2, v1
	s_add_u32 s2, s6, s2
	v_readlane_b32 s6, v252, 44
	v_cndmask_b32_e32 v2, v216, v2, vcc
	v_lshlrev_b32_e32 v38, 2, v2
	v_xor_b32_e32 v2, 32, v216
	s_addc_u32 s7, s7, s6
	v_cmp_lt_i32_e32 vcc, v2, v1
	s_add_u32 s6, s2, 0x1d4e8000
	s_addc_u32 s7, s7, 0
	v_cndmask_b32_e32 v1, v216, v2, vcc
	v_lshlrev_b32_e32 v39, 2, v1
	v_ashrrev_i32_e32 v1, 31, v0
	s_ashr_i32 s9, s8, 31
	v_lshl_add_u64 v[0:1], v[0:1], 0, s[8:9]
	v_lshlrev_b32_e32 v4, 4, v3
	v_lshlrev_b64 v[12:13], 12, v[0:1]
	v_mov_b32_e32 v5, v129
	v_or_b32_e32 v12, v12, v4
	v_lshlrev_b64 v[0:1], 11, v[0:1]
	v_lshlrev_b32_e32 v2, 2, v3
	v_lshl_add_u64 v[16:17], s[12:13], 0, v[4:5]
	v_lshl_add_u64 v[4:5], s[16:17], 0, v[12:13]
	s_mov_b64 s[8:9], 0xc00
	v_lshl_or_b32 v0, v3, 3, v0
	v_or_b32_e32 v6, 0x100, v2
	v_or_b32_e32 v8, 0x200, v2
	v_or_b32_e32 v10, 0x300, v2
	v_lshl_add_u64 v[18:19], v[4:5], 0, s[8:9]
	v_lshl_add_u64 v[0:1], s[10:11], 0, v[0:1]
	s_mov_b64 s[8:9], 0xdd20400
	v_lshl_add_u64 v[20:21], v[0:1], 0, s[8:9]
	s_mov_b64 s[8:9], 0
	v_lshlrev_b32_e32 v128, 2, v2
	v_lshlrev_b32_e32 v22, 2, v6
	v_lshlrev_b32_e32 v24, 2, v8
	v_lshlrev_b32_e32 v26, 2, v10
	global_load_dwordx4 v[180:183], v[18:19], off offset:-3072
	global_load_dwordx4 v[184:187], v[18:19], off offset:-2048
	global_load_dwordx4 v[188:191], v[18:19], off offset:-1024
	global_load_dwordx4 v[192:195], v[18:19], off
	v_lshl_add_u64 v[18:19], v[18:19], 0, s[76:77]
	global_load_dwordx4 v[130:133], v[16:17], off
	global_load_dwordx4 v[134:137], v[16:17], off offset:1024
	global_load_dwordx4 v[138:141], v[16:17], off offset:2048
	global_load_dwordx4 v[142:145], v[16:17], off offset:3072
.LBB0_218:
	s_waitcnt vmcnt(4)
	v_mov_b32_e32 v12, v180
	v_mov_b32_e32 v13, v181
	v_mov_b32_e32 v14, v182
	v_mov_b32_e32 v15, v183
	v_mov_b32_e32 v8, v184
	v_mov_b32_e32 v9, v185
	v_mov_b32_e32 v10, v186
	v_mov_b32_e32 v11, v187
	v_mov_b32_e32 v4, v188
	v_mov_b32_e32 v5, v189
	v_mov_b32_e32 v6, v190
	v_mov_b32_e32 v7, v191
	v_mov_b32_e32 v0, v192
	v_mov_b32_e32 v1, v193
	v_mov_b32_e32 v2, v194
	v_mov_b32_e32 v3, v195
	v_add_u32_e32 v196, 0xfffff000, v29
	v_ashrrev_i32_e32 v196, 12, v196
	v_mad_i32_i24 v196, v196, s81, s81
	v_cmp_lt_i32_e32 vcc, s82, v29
	v_mov_b32_e32 v27, v129
	v_mov_b32_e32 v25, v129
	s_nop 1
	v_cndmask_b32_e32 v196, 0, v196, vcc
	v_ashrrev_i32_e32 v197, 31, v196
	v_lshl_add_u64 v[32:33], v[196:197], 2, s[6:7]
	v_lshl_add_u64 v[30:31], v[32:33], 0, s[18:19]
	v_lshl_add_u64 v[198:199], v[30:31], 0, v[128:129]
	v_lshl_add_u64 v[32:33], v[32:33], 0, v[128:129]
	global_load_dwordx4 v[146:149], v[198:199], off
	global_load_dwordx4 v[162:165], v[32:33], off
	global_load_dwordx4 v[150:153], v[198:199], off offset:1024
	global_load_dwordx4 v[166:169], v[32:33], off offset:1024
	global_load_dwordx4 v[154:157], v[198:199], off offset:2048
	global_load_dwordx4 v[170:173], v[32:33], off offset:2048
	global_load_dwordx4 v[158:161], v[198:199], off offset:3072
	global_load_dwordx4 v[174:177], v[32:33], off offset:3072
	global_load_dwordx4 v[180:183], v[18:19], off offset:-3072
	global_load_dwordx4 v[184:187], v[18:19], off offset:-2048
	global_load_dwordx4 v[188:191], v[18:19], off offset:-1024
	global_load_dwordx4 v[192:195], v[18:19], off
	v_lshl_add_u64 v[18:19], v[18:19], 0, s[76:77]
	v_mov_b32_e32 v40, v13
	v_mov_b32_e32 v41, v9
	v_mov_b32_e32 v42, v12
	v_mov_b32_e32 v43, v8
	v_pk_mul_f32 v[40:41], v[40:41], v[40:41]
	s_nop 0
	v_pk_fma_f32 v[42:43], v[42:43], v[42:43], v[40:41]
	v_mov_b32_e32 v40, v14
	v_mov_b32_e32 v41, v10
	v_pk_fma_f32 v[42:43], v[40:41], v[40:41], v[42:43]
	v_mov_b32_e32 v40, v15
	v_mov_b32_e32 v41, v11
	v_pk_fma_f32 v[42:43], v[40:41], v[40:41], v[42:43]
	s_nop 0
	v_add_f32_e32 v23, v42, v43
	v_mov_b32_e32 v42, v5
	v_mov_b32_e32 v43, v1
	v_mov_b32_e32 v40, v4
	v_mov_b32_e32 v41, v0
	v_pk_mul_f32 v[42:43], v[42:43], v[42:43]
	s_nop 0
	v_pk_fma_f32 v[40:41], v[40:41], v[40:41], v[42:43]
	v_mov_b32_e32 v42, v6
	v_mov_b32_e32 v43, v2
	v_pk_fma_f32 v[40:41], v[42:43], v[42:43], v[40:41]
	v_mov_b32_e32 v42, v7
	v_mov_b32_e32 v43, v3
	v_pk_fma_f32 v[40:41], v[42:43], v[42:43], v[40:41]
	s_nop 0
	v_add_f32_e32 v23, v23, v40
	v_add_f32_e32 v23, v23, v41
	ds_bpermute_b32 v25, v34, v23
	s_waitcnt lgkmcnt(0)
	v_add_f32_e32 v23, v23, v25
	ds_bpermute_b32 v25, v35, v23
	s_waitcnt lgkmcnt(0)
	v_add_f32_e32 v23, v23, v25
	ds_bpermute_b32 v25, v36, v23
	s_waitcnt lgkmcnt(0)
	v_add_f32_e32 v23, v23, v25
	ds_bpermute_b32 v25, v37, v23
	s_waitcnt lgkmcnt(0)
	v_add_f32_e32 v23, v23, v25
	ds_bpermute_b32 v25, v38, v23
	s_waitcnt lgkmcnt(0)
	v_add_f32_e32 v23, v23, v25
	ds_bpermute_b32 v25, v39, v23
	s_waitcnt lgkmcnt(0)
	v_add_f32_e32 v23, v23, v25
	v_fmamk_f32 v23, v23, 0x3a800000, v206
	v_cmp_gt_f32_e32 vcc, s83, v23
	v_mul_f32_e32 v25, 0x4b800000, v23
	s_nop 0
	v_cndmask_b32_e32 v23, v23, v25, vcc
	v_rsq_f32_e32 v23, v23
	s_nop 0
	v_mul_f32_e32 v25, 0x45800000, v23
	v_cndmask_b32_e32 v28, v23, v25, vcc
	v_mov_b32_e32 v23, v129
	v_mov_b32_e32 v25, v129
	v_pk_mul_f32 v[12:13], v[12:13], v[28:29] op_sel_hi:[1,0]
	v_pk_mul_f32 v[14:15], v[14:15], v[28:29] op_sel_hi:[1,0]
	v_pk_mul_f32 v[8:9], v[8:9], v[28:29] op_sel_hi:[1,0]
	v_pk_mul_f32 v[10:11], v[10:11], v[28:29] op_sel_hi:[1,0]
	v_pk_mul_f32 v[4:5], v[4:5], v[28:29] op_sel_hi:[1,0]
	v_pk_mul_f32 v[6:7], v[6:7], v[28:29] op_sel_hi:[1,0]
	v_pk_mul_f32 v[0:1], v[0:1], v[28:29] op_sel_hi:[1,0]
	v_pk_mul_f32 v[2:3], v[2:3], v[28:29] op_sel_hi:[1,0]
	v_add_u32_e32 v29, s66, v29
	v_cmp_lt_i32_e32 vcc, s84, v29
	s_or_b64 s[8:9], vcc, s[8:9]
	s_waitcnt vmcnt(4)
	v_pk_mul_f32 v[12:13], v[130:131], v[12:13]
	v_pk_add_f32 v[40:41], v[146:147], 1.0 op_sel_hi:[1,0]
	v_pk_mul_f32 v[14:15], v[132:133], v[14:15]
	v_pk_fma_f32 v[12:13], v[40:41], v[12:13], v[162:163]
	v_pk_add_f32 v[40:41], v[148:149], 1.0 op_sel_hi:[1,0]
	v_cvt_pk_bf16_f32 v12, v12, v13
	v_pk_fma_f32 v[14:15], v[40:41], v[14:15], v[164:165]
	s_nop 0
	v_cvt_pk_bf16_f32 v13, v14, v15
	global_store_dwordx2 v[20:21], v[12:13], off offset:-1024
	v_pk_mul_f32 v[8:9], v[134:135], v[8:9]
	v_pk_add_f32 v[40:41], v[150:151], 1.0 op_sel_hi:[1,0]
	v_pk_mul_f32 v[10:11], v[136:137], v[10:11]
	v_pk_fma_f32 v[8:9], v[40:41], v[8:9], v[166:167]
	v_pk_add_f32 v[40:41], v[152:153], 1.0 op_sel_hi:[1,0]
	v_cvt_pk_bf16_f32 v8, v8, v9
	v_pk_fma_f32 v[10:11], v[40:41], v[10:11], v[168:169]
	s_nop 0
	v_cvt_pk_bf16_f32 v9, v10, v11
	global_store_dwordx2 v[20:21], v[8:9], off offset:-512
	v_pk_mul_f32 v[4:5], v[138:139], v[4:5]
	v_pk_add_f32 v[40:41], v[154:155], 1.0 op_sel_hi:[1,0]
	v_pk_mul_f32 v[6:7], v[140:141], v[6:7]
	v_pk_fma_f32 v[4:5], v[40:41], v[4:5], v[170:171]
	v_pk_add_f32 v[40:41], v[156:157], 1.0 op_sel_hi:[1,0]
	v_cvt_pk_bf16_f32 v4, v4, v5
	v_pk_fma_f32 v[6:7], v[40:41], v[6:7], v[172:173]
	s_nop 0
	v_cvt_pk_bf16_f32 v5, v6, v7
	global_store_dwordx2 v[20:21], v[4:5], off
	v_pk_mul_f32 v[0:1], v[142:143], v[0:1]
	v_pk_add_f32 v[40:41], v[158:159], 1.0 op_sel_hi:[1,0]
	v_pk_mul_f32 v[2:3], v[144:145], v[2:3]
	v_pk_fma_f32 v[0:1], v[40:41], v[0:1], v[174:175]
	v_pk_add_f32 v[40:41], v[160:161], 1.0 op_sel_hi:[1,0]
	v_cvt_pk_bf16_f32 v0, v0, v1
	v_pk_fma_f32 v[2:3], v[40:41], v[2:3], v[176:177]
	s_nop 0
	v_cvt_pk_bf16_f32 v1, v2, v3
	global_store_dwordx2 v[20:21], v[0:1], off offset:512
	v_lshl_add_u64 v[20:21], v[20:21], 0, s[38:39]
	s_andn2_b64 exec, exec, s[8:9]
	s_cbranch_execnz .LBB0_218
	s_waitcnt vmcnt(0)

.LBB0_1991:
	s_or_b64 exec, exec, s[4:5]
	s_mov_b64 s[8:9], s[0:1]
	s_mov_b64 s[12:13], s[0:1]
	s_mov_b64 s[16:17], s[0:1]
	s_mov_b64 s[14:15], s[0:1]
	v_mov_b32_e32 v1, v205
	s_mov_b32 s2, s61
	s_waitcnt lgkmcnt(0)
	v_mov_b32_e32 v0, v205
	s_barrier
	s_lshl_b32 s10, s2, 2
	v_ashrrev_i32_e32 v0, 6, v0
	v_add_u32_e32 v29, s10, v0
	s_movk_i32 s2, 0x5000
	v_cmp_gt_i32_e32 vcc, s2, v29
	s_and_saveexec_b64 s[4:5], vcc
	s_cbranch_execz .LBB0_1994
	v_and_b32_e32 v3, 63, v1
	v_and_b32_e32 v1, 64, v216
	v_add_u32_e32 v1, 64, v1
	v_xor_b32_e32 v2, 1, v216
	v_cmp_lt_i32_e32 vcc, v2, v1
	s_load_dwordx2 s[16:17], s[16:17], 0xd8
	s_nop 0
	s_load_dwordx2 s[18:19], s[8:9], 0x100
	s_nop 0
	s_load_dwordx2 s[12:13], s[12:13], 0x108
	s_nop 0
	s_load_dwordx2 s[8:9], s[14:15], 0x108
	v_cndmask_b32_e32 v2, v216, v2, vcc
	v_lshlrev_b32_e32 v34, 2, v2
	v_xor_b32_e32 v2, 2, v216
	v_cmp_lt_i32_e32 vcc, v2, v1
	v_readlane_b32 s14, v252, 40
	v_readlane_b32 s15, v252, 41
	v_cndmask_b32_e32 v2, v216, v2, vcc
	v_lshlrev_b32_e32 v35, 2, v2
	v_xor_b32_e32 v2, 4, v216
	v_cmp_lt_i32_e32 vcc, v2, v1
	s_lshl_b64 s[14:15], s[14:15], 2
	s_waitcnt lgkmcnt(0)
	s_add_u32 s14, s16, s14
	v_cndmask_b32_e32 v2, v216, v2, vcc
	v_lshlrev_b32_e32 v36, 2, v2
	v_xor_b32_e32 v2, 8, v216
	v_cmp_lt_i32_e32 vcc, v2, v1
	s_addc_u32 s15, s17, s15
	v_readlane_b32 s2, v252, 45
	v_cndmask_b32_e32 v2, v216, v2, vcc
	v_lshlrev_b32_e32 v37, 2, v2
	v_xor_b32_e32 v2, 16, v216
	v_cmp_lt_i32_e32 vcc, v2, v1
	s_add_u32 s2, s8, s2
	v_readlane_b32 s8, v252, 44
	v_cndmask_b32_e32 v2, v216, v2, vcc
	v_lshlrev_b32_e32 v38, 2, v2
	v_xor_b32_e32 v2, 32, v216
	s_addc_u32 s9, s9, s8
	v_cmp_lt_i32_e32 vcc, v2, v1
	s_add_u32 s8, s2, 0x1d4eb000
	s_addc_u32 s9, s9, 0
	v_cndmask_b32_e32 v1, v216, v2, vcc
	v_lshlrev_b32_e32 v39, 2, v1
	v_ashrrev_i32_e32 v1, 31, v0
	s_ashr_i32 s11, s10, 31
	v_lshl_add_u64 v[0:1], v[0:1], 0, s[10:11]
	v_lshlrev_b32_e32 v4, 4, v3
	v_lshlrev_b64 v[12:13], 12, v[0:1]
	v_mov_b32_e32 v5, v129
	v_or_b32_e32 v12, v12, v4
	v_lshlrev_b64 v[0:1], 11, v[0:1]
	v_lshlrev_b32_e32 v2, 2, v3
	v_lshl_add_u64 v[16:17], s[14:15], 0, v[4:5]
	v_lshl_add_u64 v[4:5], s[18:19], 0, v[12:13]
	s_mov_b64 s[10:11], 0xc00
	v_lshl_or_b32 v0, v3, 3, v0
	v_or_b32_e32 v6, 0x100, v2
	v_or_b32_e32 v8, 0x200, v2
	v_or_b32_e32 v10, 0x300, v2
	v_lshl_add_u64 v[18:19], v[4:5], 0, s[10:11]
	v_lshl_add_u64 v[0:1], s[12:13], 0, v[0:1]
	s_mov_b64 s[10:11], 0xdd20400
	v_lshl_add_u64 v[20:21], v[0:1], 0, s[10:11]
	s_mov_b64 s[10:11], 0
	v_lshlrev_b32_e32 v128, 2, v2
	v_lshlrev_b32_e32 v22, 2, v6
	v_lshlrev_b32_e32 v24, 2, v8
	v_lshlrev_b32_e32 v26, 2, v10
	global_load_dwordx4 v[180:183], v[18:19], off offset:-3072
	global_load_dwordx4 v[184:187], v[18:19], off offset:-2048
	global_load_dwordx4 v[188:191], v[18:19], off offset:-1024
	global_load_dwordx4 v[192:195], v[18:19], off
	v_lshl_add_u64 v[18:19], v[18:19], 0, s[76:77]
	global_load_dwordx4 v[130:133], v[16:17], off
	global_load_dwordx4 v[134:137], v[16:17], off offset:1024
	global_load_dwordx4 v[138:141], v[16:17], off offset:2048
	global_load_dwordx4 v[142:145], v[16:17], off offset:3072
.LBB0_1993:
	s_waitcnt vmcnt(4)
	v_mov_b32_e32 v12, v180
	v_mov_b32_e32 v13, v181
	v_mov_b32_e32 v14, v182
	v_mov_b32_e32 v15, v183
	v_mov_b32_e32 v8, v184
	v_mov_b32_e32 v9, v185
	v_mov_b32_e32 v10, v186
	v_mov_b32_e32 v11, v187
	v_mov_b32_e32 v4, v188
	v_mov_b32_e32 v5, v189
	v_mov_b32_e32 v6, v190
	v_mov_b32_e32 v7, v191
	v_mov_b32_e32 v0, v192
	v_mov_b32_e32 v1, v193
	v_mov_b32_e32 v2, v194
	v_mov_b32_e32 v3, v195
	v_add_u32_e32 v196, 0xfffff000, v29
	v_ashrrev_i32_e32 v196, 12, v196
	v_mad_i32_i24 v196, v196, s81, s81
	v_cmp_lt_i32_e32 vcc, s82, v29
	v_mov_b32_e32 v27, v129
	v_mov_b32_e32 v25, v129
	s_nop 1
	v_cndmask_b32_e32 v196, 0, v196, vcc
	v_ashrrev_i32_e32 v197, 31, v196
	v_lshl_add_u64 v[32:33], v[196:197], 2, s[8:9]
	v_lshl_add_u64 v[30:31], v[32:33], 0, s[36:37]
	v_lshl_add_u64 v[198:199], v[30:31], 0, v[128:129]
	v_lshl_add_u64 v[32:33], v[32:33], 0, v[128:129]
	global_load_dwordx4 v[146:149], v[198:199], off
	global_load_dwordx4 v[162:165], v[32:33], off
	global_load_dwordx4 v[150:153], v[198:199], off offset:1024
	global_load_dwordx4 v[166:169], v[32:33], off offset:1024
	global_load_dwordx4 v[154:157], v[198:199], off offset:2048
	global_load_dwordx4 v[170:173], v[32:33], off offset:2048
	global_load_dwordx4 v[158:161], v[198:199], off offset:3072
	global_load_dwordx4 v[174:177], v[32:33], off offset:3072
	global_load_dwordx4 v[180:183], v[18:19], off offset:-3072
	global_load_dwordx4 v[184:187], v[18:19], off offset:-2048
	global_load_dwordx4 v[188:191], v[18:19], off offset:-1024
	global_load_dwordx4 v[192:195], v[18:19], off
	v_lshl_add_u64 v[18:19], v[18:19], 0, s[76:77]
	v_mov_b32_e32 v40, v13
	v_mov_b32_e32 v41, v9
	v_mov_b32_e32 v42, v12
	v_mov_b32_e32 v43, v8
	v_pk_mul_f32 v[40:41], v[40:41], v[40:41]
	s_nop 0
	v_pk_fma_f32 v[42:43], v[42:43], v[42:43], v[40:41]
	v_mov_b32_e32 v40, v14
	v_mov_b32_e32 v41, v10
	v_pk_fma_f32 v[42:43], v[40:41], v[40:41], v[42:43]
	v_mov_b32_e32 v40, v15
	v_mov_b32_e32 v41, v11
	v_pk_fma_f32 v[42:43], v[40:41], v[40:41], v[42:43]
	s_nop 0
	v_add_f32_e32 v23, v42, v43
	v_mov_b32_e32 v42, v5
	v_mov_b32_e32 v43, v1
	v_mov_b32_e32 v40, v4
	v_mov_b32_e32 v41, v0
	v_pk_mul_f32 v[42:43], v[42:43], v[42:43]
	s_nop 0
	v_pk_fma_f32 v[40:41], v[40:41], v[40:41], v[42:43]
	v_mov_b32_e32 v42, v6
	v_mov_b32_e32 v43, v2
	v_pk_fma_f32 v[40:41], v[42:43], v[42:43], v[40:41]
	v_mov_b32_e32 v42, v7
	v_mov_b32_e32 v43, v3
	v_pk_fma_f32 v[40:41], v[42:43], v[42:43], v[40:41]
	s_nop 0
	v_add_f32_e32 v23, v23, v40
	v_add_f32_e32 v23, v23, v41
	ds_bpermute_b32 v25, v34, v23
	s_waitcnt lgkmcnt(0)
	v_add_f32_e32 v23, v23, v25
	ds_bpermute_b32 v25, v35, v23
	s_waitcnt lgkmcnt(0)
	v_add_f32_e32 v23, v23, v25
	ds_bpermute_b32 v25, v36, v23
	s_waitcnt lgkmcnt(0)
	v_add_f32_e32 v23, v23, v25
	ds_bpermute_b32 v25, v37, v23
	s_waitcnt lgkmcnt(0)
	v_add_f32_e32 v23, v23, v25
	ds_bpermute_b32 v25, v38, v23
	s_waitcnt lgkmcnt(0)
	v_add_f32_e32 v23, v23, v25
	ds_bpermute_b32 v25, v39, v23
	s_waitcnt lgkmcnt(0)
	v_add_f32_e32 v23, v23, v25
	v_fmamk_f32 v23, v23, 0x3a800000, v206
	v_cmp_gt_f32_e32 vcc, s83, v23
	v_mul_f32_e32 v25, 0x4b800000, v23
	s_nop 0
	v_cndmask_b32_e32 v23, v23, v25, vcc
	v_rsq_f32_e32 v23, v23
	s_nop 0
	v_mul_f32_e32 v25, 0x45800000, v23
	v_cndmask_b32_e32 v28, v23, v25, vcc
	v_mov_b32_e32 v23, v129
	v_mov_b32_e32 v25, v129
	v_pk_mul_f32 v[12:13], v[12:13], v[28:29] op_sel_hi:[1,0]
	v_pk_mul_f32 v[14:15], v[14:15], v[28:29] op_sel_hi:[1,0]
	v_pk_mul_f32 v[8:9], v[8:9], v[28:29] op_sel_hi:[1,0]
	v_pk_mul_f32 v[10:11], v[10:11], v[28:29] op_sel_hi:[1,0]
	v_pk_mul_f32 v[4:5], v[4:5], v[28:29] op_sel_hi:[1,0]
	v_pk_mul_f32 v[6:7], v[6:7], v[28:29] op_sel_hi:[1,0]
	v_pk_mul_f32 v[0:1], v[0:1], v[28:29] op_sel_hi:[1,0]
	v_pk_mul_f32 v[2:3], v[2:3], v[28:29] op_sel_hi:[1,0]
	v_add_u32_e32 v29, s66, v29
	v_cmp_lt_i32_e32 vcc, s84, v29
	s_or_b64 s[10:11], vcc, s[10:11]
	s_waitcnt vmcnt(4)
	v_pk_mul_f32 v[12:13], v[130:131], v[12:13]
	v_pk_add_f32 v[40:41], v[146:147], 1.0 op_sel_hi:[1,0]
	v_pk_mul_f32 v[14:15], v[132:133], v[14:15]
	v_pk_fma_f32 v[12:13], v[40:41], v[12:13], v[162:163]
	v_pk_add_f32 v[40:41], v[148:149], 1.0 op_sel_hi:[1,0]
	v_cvt_pk_bf16_f32 v12, v12, v13
	v_pk_fma_f32 v[14:15], v[40:41], v[14:15], v[164:165]
	s_nop 0
	v_cvt_pk_bf16_f32 v13, v14, v15
	global_store_dwordx2 v[20:21], v[12:13], off offset:-1024
	v_pk_mul_f32 v[8:9], v[134:135], v[8:9]
	v_pk_add_f32 v[40:41], v[150:151], 1.0 op_sel_hi:[1,0]
	v_pk_mul_f32 v[10:11], v[136:137], v[10:11]
	v_pk_fma_f32 v[8:9], v[40:41], v[8:9], v[166:167]
	v_pk_add_f32 v[40:41], v[152:153], 1.0 op_sel_hi:[1,0]
	v_cvt_pk_bf16_f32 v8, v8, v9
	v_pk_fma_f32 v[10:11], v[40:41], v[10:11], v[168:169]
	s_nop 0
	v_cvt_pk_bf16_f32 v9, v10, v11
	global_store_dwordx2 v[20:21], v[8:9], off offset:-512
	v_pk_mul_f32 v[4:5], v[138:139], v[4:5]
	v_pk_add_f32 v[40:41], v[154:155], 1.0 op_sel_hi:[1,0]
	v_pk_mul_f32 v[6:7], v[140:141], v[6:7]
	v_pk_fma_f32 v[4:5], v[40:41], v[4:5], v[170:171]
	v_pk_add_f32 v[40:41], v[156:157], 1.0 op_sel_hi:[1,0]
	v_cvt_pk_bf16_f32 v4, v4, v5
	v_pk_fma_f32 v[6:7], v[40:41], v[6:7], v[172:173]
	s_nop 0
	v_cvt_pk_bf16_f32 v5, v6, v7
	global_store_dwordx2 v[20:21], v[4:5], off
	v_pk_mul_f32 v[0:1], v[142:143], v[0:1]
	v_pk_add_f32 v[40:41], v[158:159], 1.0 op_sel_hi:[1,0]
	v_pk_mul_f32 v[2:3], v[144:145], v[2:3]
	v_pk_fma_f32 v[0:1], v[40:41], v[0:1], v[174:175]
	v_pk_add_f32 v[40:41], v[160:161], 1.0 op_sel_hi:[1,0]
	v_cvt_pk_bf16_f32 v0, v0, v1
	v_pk_fma_f32 v[2:3], v[40:41], v[2:3], v[176:177]
	s_nop 0
	v_cvt_pk_bf16_f32 v1, v2, v3
	global_store_dwordx2 v[20:21], v[0:1], off offset:512
	v_lshl_add_u64 v[20:21], v[20:21], 0, s[38:39]
	s_andn2_b64 exec, exec, s[10:11]
	s_cbranch_execnz .LBB0_1993
	s_waitcnt vmcnt(0)
